# speedup vs baseline: 1.0012x; 1.0012x over previous
; #define opaque_tid() opaque_tid_(WV)
; __device__ __forceinline__ void mixer_phase(const int WV, const Params& P, int layer) {
;     ...
;   wait_flag_ge(pdone, gridDim.x - 64);
;   __syncthreads();
;   unsigned* ctr = (unsigned*)(P.ws + OFF_CTR) + layer * 8;
;   __shared__ int s_item;
;   const int xcd = blockIdx.x & 7;
;   for (int xo = 0; xo < 8; ++xo) {
;     const int qx = (xcd + xo) & 7;
;     for (;;) {
;       __syncthreads();
;       if (opaque_tid() == 0) s_item = (int)atomicAdd(ctr + qx, 1u);
;       __syncthreads();
;       int item = s_item;
;       if (item >= 256) break;
;       attn_item(WV, P, (item >> 6) * 8 + qx, 63 - (item & 63));
.LBB0_361:
	s_mov_b32 s22, 0
	v_readlane_b32 s23, v252, 35
	buffer_inv sc1
	s_barrier
	v_readfirstlane_b32 s4, v162
	s_nop 3
	s_cmp_ge_u32 s4, 0x100
	s_cbranch_scc1 .Laprio_skip
	s_setprio 1
.Laprio_skip:
	s_branch .LBB0_363
.LBB0_362:
	s_add_i32 s22, s22, 1
	s_add_i32 s23, s23, 1
	s_cmp_lg_u32 s22, 8
	s_cbranch_scc0 .LBB0_404

; __device__ __forceinline__ void mixer_phase(const int WV, const Params& P, int layer) {
;     ...
;   __syncthreads();
.LBB0_404:
	s_setprio 0
	s_waitcnt lgkmcnt(0)
	s_barrier
	s_mov_b64 s[6:7], 0
	s_mov_b64 s[4:5], -1
	s_and_b64 vcc, exec, s[0:1]
	s_cbranch_vccnz .LBB0_289
